# v1 + grid barrier: non-leader workgroups issue the L1 invalidate before polling the release word instead of after
# baseline (speedup 1.0000x reference)
; __device__ __forceinline__ unsigned xb_ld(unsigned* p)              { return __hip_atomic_load(p, __ATOMIC_RELAXED, __HIP_MEMORY_SCOPE_AGENT); }
; __device__ __forceinline__ unsigned xb_add(unsigned* p, unsigned v) { return __hip_atomic_fetch_add(p, v, __ATOMIC_RELAXED, __HIP_MEMORY_SCOPE_AGENT); }
; #define XB_SPIN(cond, bar) do { unsigned _sp = 0; while (cond) { __builtin_amdgcn_s_sleep(1); \
;     if ((++_sp & 255u) == 0u) { if (xb_ld(&(bar)[XB_TMO])) break; if (_sp > XB_SPIN_CAP) { atomicAdd(&(bar)[XB_TMO], 1u); break; } } } } while (0)
; __device__ __forceinline__ void xcd_barrier(const XcdBarrier& b) {
;     ...
;         const unsigned old = xb_add(&bar[XB_XSUB(b.x)], 1u);
;         const unsigned gen = old / nloc;
;         if (old + 1u == (gen + 1u) * nloc) {
;             __builtin_amdgcn_fence(__ATOMIC_RELEASE, "agent");
;             asm volatile("s_waitcnt vmcnt(0)" ::: "memory");
;             const unsigned og = xb_add(&bar[XB_TOP], 1u);
;             const unsigned tg = og / nx;
;             if (og + 1u == (tg + 1u) * nx) xb_add(&bar[XB_TOPGEN], 1u);
;             else XB_SPIN(xb_ld(&bar[XB_TOPGEN]) == tg, bar);
;             __builtin_amdgcn_fence(__ATOMIC_ACQUIRE, "agent");
;             xb_add(&bar[XB_XGEN(b.x)], 1u);
;             asm volatile("s_waitcnt vmcnt(0)" ::: "memory");
;         } else {
;             XB_SPIN(xb_ld(&bar[XB_XGEN(b.x)]) == gen, bar);
;             __builtin_amdgcn_fence(__ATOMIC_ACQUIRE, "agent");
;             asm volatile("s_waitcnt vmcnt(0)" ::: "memory");
.LBB0_111:
	s_or_b64 exec, exec, s[10:11]
	v_cvt_f32_u32_e32 v6, v4
	s_waitcnt vmcnt(0)
	v_readfirstlane_b32 s8, v5
	v_sub_u32_e32 v5, 0, v4
	v_rcp_iflag_f32_e32 v6, v6
	v_add_u32_e32 v7, s8, v3
	v_mul_f32_e32 v6, 0x4f7ffffe, v6
	v_cvt_u32_f32_e32 v6, v6
	v_mul_lo_u32 v3, v5, v6
	v_mul_hi_u32 v3, v6, v3
	v_add_u32_e32 v3, v6, v3
	v_mul_hi_u32 v3, v7, v3
	v_mul_lo_u32 v5, v3, v4
	v_sub_u32_e32 v5, v7, v5
	v_add_u32_e32 v6, 1, v3
	v_cmp_ge_u32_e32 vcc, v5, v4
	s_nop 1
	v_cndmask_b32_e32 v3, v3, v6, vcc
	v_sub_u32_e32 v6, v5, v4
	v_cndmask_b32_e32 v5, v5, v6, vcc
	v_add_u32_e32 v6, 1, v3
	v_cmp_ge_u32_e32 vcc, v5, v4
	v_add_u32_e32 v5, 1, v7
	s_nop 0
	v_cndmask_b32_e32 v3, v3, v6, vcc
	v_mul_lo_u32 v6, v4, v3
	v_add_u32_e32 v4, v6, v4
	v_cmp_ne_u32_e32 vcc, v5, v4
	s_and_saveexec_b64 s[8:9], vcc
	s_xor_b64 s[8:9], exec, s[8:9]
	s_cbranch_execz .LBB0_125
	s_waitcnt lgkmcnt(0)
	buffer_inv sc1
	v_mov_b32_e32 v2, 0x2000
	global_load_dword v2, v2, s[4:5] offset:1024 sc1
	s_add_u32 s14, s4, 0x2400
	s_addc_u32 s15, s5, 0
	s_waitcnt vmcnt(0)
	v_cmp_eq_u32_e32 vcc, v2, v3
	s_and_saveexec_b64 s[10:11], vcc
	s_cbranch_execz .LBB0_124
	s_add_u32 s12, s88, 0x4200
	s_addc_u32 s13, s89, 0
	s_mov_b32 s26, 1
	s_mov_b64 s[16:17], 0
	v_mov_b32_e32 v2, 0
	s_branch .LBB0_115

; __device__ __forceinline__ unsigned xb_ld(unsigned* p)              { return __hip_atomic_load(p, __ATOMIC_RELAXED, __HIP_MEMORY_SCOPE_AGENT); }
; #define XB_SPIN(cond, bar) do { unsigned _sp = 0; while (cond) { __builtin_amdgcn_s_sleep(1); \
;     if ((++_sp & 255u) == 0u) { if (xb_ld(&(bar)[XB_TMO])) break; if (_sp > XB_SPIN_CAP) { atomicAdd(&(bar)[XB_TMO], 1u); break; } } } } while (0)
; __device__ __forceinline__ void xcd_barrier(const XcdBarrier& b) {
;     ...
;             XB_SPIN(xb_ld(&bar[XB_XGEN(b.x)]) == gen, bar);
;             __builtin_amdgcn_fence(__ATOMIC_ACQUIRE, "agent");
;             asm volatile("s_waitcnt vmcnt(0)" ::: "memory");
.LBB0_124:
	s_or_b64 exec, exec, s[10:11]
	s_waitcnt vmcnt(0)
	s_waitcnt vmcnt(0)

; __device__ __forceinline__ unsigned xb_ld(unsigned* p)              { return __hip_atomic_load(p, __ATOMIC_RELAXED, __HIP_MEMORY_SCOPE_AGENT); }
; __device__ __forceinline__ unsigned xb_add(unsigned* p, unsigned v) { return __hip_atomic_fetch_add(p, v, __ATOMIC_RELAXED, __HIP_MEMORY_SCOPE_AGENT); }
; #define XB_SPIN(cond, bar) do { unsigned _sp = 0; while (cond) { __builtin_amdgcn_s_sleep(1); \
;     if ((++_sp & 255u) == 0u) { if (xb_ld(&(bar)[XB_TMO])) break; if (_sp > XB_SPIN_CAP) { atomicAdd(&(bar)[XB_TMO], 1u); break; } } } } while (0)
; __device__ __forceinline__ void xcd_barrier(const XcdBarrier& b) {
;     ...
;         const unsigned old = xb_add(&bar[XB_XSUB(b.x)], 1u);
;         const unsigned gen = old / nloc;
;         if (old + 1u == (gen + 1u) * nloc) {
;             __builtin_amdgcn_fence(__ATOMIC_RELEASE, "agent");
;             asm volatile("s_waitcnt vmcnt(0)" ::: "memory");
;             const unsigned og = xb_add(&bar[XB_TOP], 1u);
;             const unsigned tg = og / nx;
;             if (og + 1u == (tg + 1u) * nx) xb_add(&bar[XB_TOPGEN], 1u);
;             else XB_SPIN(xb_ld(&bar[XB_TOPGEN]) == tg, bar);
;             __builtin_amdgcn_fence(__ATOMIC_ACQUIRE, "agent");
;             xb_add(&bar[XB_XGEN(b.x)], 1u);
;             asm volatile("s_waitcnt vmcnt(0)" ::: "memory");
;         } else {
;             XB_SPIN(xb_ld(&bar[XB_XGEN(b.x)]) == gen, bar);
;             __builtin_amdgcn_fence(__ATOMIC_ACQUIRE, "agent");
;             asm volatile("s_waitcnt vmcnt(0)" ::: "memory");
.LBB0_174:
	s_or_b64 exec, exec, s[8:9]
	v_cvt_f32_u32_e32 v6, v4
	s_waitcnt vmcnt(0)
	v_readfirstlane_b32 s6, v5
	v_sub_u32_e32 v5, 0, v4
	v_rcp_iflag_f32_e32 v6, v6
	v_add_u32_e32 v7, s6, v3
	v_mul_f32_e32 v6, 0x4f7ffffe, v6
	v_cvt_u32_f32_e32 v6, v6
	v_mul_lo_u32 v3, v5, v6
	v_mul_hi_u32 v3, v6, v3
	v_add_u32_e32 v3, v6, v3
	v_mul_hi_u32 v3, v7, v3
	v_mul_lo_u32 v5, v3, v4
	v_sub_u32_e32 v5, v7, v5
	v_add_u32_e32 v6, 1, v3
	v_cmp_ge_u32_e32 vcc, v5, v4
	s_nop 1
	v_cndmask_b32_e32 v3, v3, v6, vcc
	v_sub_u32_e32 v6, v5, v4
	v_cndmask_b32_e32 v5, v5, v6, vcc
	v_add_u32_e32 v6, 1, v3
	v_cmp_ge_u32_e32 vcc, v5, v4
	v_add_u32_e32 v5, 1, v7
	s_nop 0
	v_cndmask_b32_e32 v3, v3, v6, vcc
	v_mul_lo_u32 v6, v4, v3
	v_add_u32_e32 v4, v6, v4
	v_cmp_ne_u32_e32 vcc, v5, v4
	s_and_saveexec_b64 s[6:7], vcc
	s_xor_b64 s[6:7], exec, s[6:7]
	s_cbranch_execz .LBB0_188
	s_waitcnt lgkmcnt(0)
	buffer_inv sc1
	v_mov_b32_e32 v2, 0x2000
	global_load_dword v2, v2, s[4:5] offset:1024 sc1
	s_add_u32 s12, s4, 0x2400
	s_addc_u32 s13, s5, 0
	s_waitcnt vmcnt(0)
	v_cmp_eq_u32_e32 vcc, v2, v3
	s_and_saveexec_b64 s[8:9], vcc
	s_cbranch_execz .LBB0_187
	s_add_u32 s10, s88, 0x4200
	s_addc_u32 s11, s89, 0
	s_mov_b32 s24, 1
	s_mov_b64 s[14:15], 0
	v_mov_b32_e32 v2, 0
	s_branch .LBB0_178

; __device__ __forceinline__ unsigned xb_ld(unsigned* p)              { return __hip_atomic_load(p, __ATOMIC_RELAXED, __HIP_MEMORY_SCOPE_AGENT); }
; #define XB_SPIN(cond, bar) do { unsigned _sp = 0; while (cond) { __builtin_amdgcn_s_sleep(1); \
;     if ((++_sp & 255u) == 0u) { if (xb_ld(&(bar)[XB_TMO])) break; if (_sp > XB_SPIN_CAP) { atomicAdd(&(bar)[XB_TMO], 1u); break; } } } } while (0)
; __device__ __forceinline__ void xcd_barrier(const XcdBarrier& b) {
;     ...
;             XB_SPIN(xb_ld(&bar[XB_XGEN(b.x)]) == gen, bar);
;             __builtin_amdgcn_fence(__ATOMIC_ACQUIRE, "agent");
;             asm volatile("s_waitcnt vmcnt(0)" ::: "memory");
.LBB0_187:
	s_or_b64 exec, exec, s[8:9]
	s_waitcnt vmcnt(0)
	s_waitcnt vmcnt(0)

; __device__ __forceinline__ unsigned xb_ld(unsigned* p)              { return __hip_atomic_load(p, __ATOMIC_RELAXED, __HIP_MEMORY_SCOPE_AGENT); }
; __device__ __forceinline__ unsigned xb_add(unsigned* p, unsigned v) { return __hip_atomic_fetch_add(p, v, __ATOMIC_RELAXED, __HIP_MEMORY_SCOPE_AGENT); }
; #define XB_SPIN(cond, bar) do { unsigned _sp = 0; while (cond) { __builtin_amdgcn_s_sleep(1); \
;     if ((++_sp & 255u) == 0u) { if (xb_ld(&(bar)[XB_TMO])) break; if (_sp > XB_SPIN_CAP) { atomicAdd(&(bar)[XB_TMO], 1u); break; } } } } while (0)
; __device__ __forceinline__ void xcd_barrier(const XcdBarrier& b) {
;     ...
;         const unsigned old = xb_add(&bar[XB_XSUB(b.x)], 1u);
;         const unsigned gen = old / nloc;
;         if (old + 1u == (gen + 1u) * nloc) {
;             __builtin_amdgcn_fence(__ATOMIC_RELEASE, "agent");
;             asm volatile("s_waitcnt vmcnt(0)" ::: "memory");
;             const unsigned og = xb_add(&bar[XB_TOP], 1u);
;             const unsigned tg = og / nx;
;             if (og + 1u == (tg + 1u) * nx) xb_add(&bar[XB_TOPGEN], 1u);
;             else XB_SPIN(xb_ld(&bar[XB_TOPGEN]) == tg, bar);
;             __builtin_amdgcn_fence(__ATOMIC_ACQUIRE, "agent");
;             xb_add(&bar[XB_XGEN(b.x)], 1u);
;             asm volatile("s_waitcnt vmcnt(0)" ::: "memory");
;         } else {
;             XB_SPIN(xb_ld(&bar[XB_XGEN(b.x)]) == gen, bar);
;             __builtin_amdgcn_fence(__ATOMIC_ACQUIRE, "agent");
;             asm volatile("s_waitcnt vmcnt(0)" ::: "memory");
.LBB0_2388:
	s_or_b64 exec, exec, s[8:9]
	v_cvt_f32_u32_e32 v5, v3
	s_waitcnt vmcnt(0)
	v_readfirstlane_b32 s6, v4
	v_sub_u32_e32 v4, 0, v3
	v_rcp_iflag_f32_e32 v5, v5
	v_add_u32_e32 v6, s6, v2
	v_mul_f32_e32 v5, 0x4f7ffffe, v5
	v_cvt_u32_f32_e32 v5, v5
	v_mul_lo_u32 v2, v4, v5
	v_mul_hi_u32 v2, v5, v2
	v_add_u32_e32 v2, v5, v2
	v_mul_hi_u32 v2, v6, v2
	v_mul_lo_u32 v4, v2, v3
	v_sub_u32_e32 v4, v6, v4
	v_add_u32_e32 v5, 1, v2
	v_cmp_ge_u32_e32 vcc, v4, v3
	s_nop 1
	v_cndmask_b32_e32 v2, v2, v5, vcc
	v_sub_u32_e32 v5, v4, v3
	v_cndmask_b32_e32 v4, v4, v5, vcc
	v_add_u32_e32 v5, 1, v2
	v_cmp_ge_u32_e32 vcc, v4, v3
	v_add_u32_e32 v4, 1, v6
	s_nop 0
	v_cndmask_b32_e32 v2, v2, v5, vcc
	v_mul_lo_u32 v5, v3, v2
	v_add_u32_e32 v3, v5, v3
	v_cmp_ne_u32_e32 vcc, v4, v3
	s_and_saveexec_b64 s[6:7], vcc
	s_xor_b64 s[6:7], exec, s[6:7]
	s_cbranch_execz .LBB0_2402
	s_waitcnt lgkmcnt(0)
	buffer_inv sc1
	v_mov_b32_e32 v1, 0x2000
	global_load_dword v1, v1, s[4:5] offset:1024 sc1
	s_add_u32 s12, s4, 0x2400
	s_addc_u32 s13, s5, 0
	s_waitcnt vmcnt(0)
	v_cmp_eq_u32_e32 vcc, v1, v2
	s_and_saveexec_b64 s[8:9], vcc
	s_cbranch_execz .LBB0_2401
	s_add_u32 s10, s88, 0x4200
	s_addc_u32 s11, s89, 0
	s_mov_b32 s24, 1
	s_mov_b64 s[14:15], 0
	v_mov_b32_e32 v1, 0
	s_branch .LBB0_2392

; __device__ __forceinline__ unsigned xb_ld(unsigned* p)              { return __hip_atomic_load(p, __ATOMIC_RELAXED, __HIP_MEMORY_SCOPE_AGENT); }
; __device__ __forceinline__ unsigned xb_add(unsigned* p, unsigned v) { return __hip_atomic_fetch_add(p, v, __ATOMIC_RELAXED, __HIP_MEMORY_SCOPE_AGENT); }
; #define XB_SPIN(cond, bar) do { unsigned _sp = 0; while (cond) { __builtin_amdgcn_s_sleep(1); \
;     if ((++_sp & 255u) == 0u) { if (xb_ld(&(bar)[XB_TMO])) break; if (_sp > XB_SPIN_CAP) { atomicAdd(&(bar)[XB_TMO], 1u); break; } } } } while (0)
; __device__ __forceinline__ void xcd_barrier(const XcdBarrier& b) {
;     ...
;         const unsigned old = xb_add(&bar[XB_XSUB(b.x)], 1u);
;         const unsigned gen = old / nloc;
;         if (old + 1u == (gen + 1u) * nloc) {
;             __builtin_amdgcn_fence(__ATOMIC_RELEASE, "agent");
;             asm volatile("s_waitcnt vmcnt(0)" ::: "memory");
;             const unsigned og = xb_add(&bar[XB_TOP], 1u);
;             const unsigned tg = og / nx;
;             if (og + 1u == (tg + 1u) * nx) xb_add(&bar[XB_TOPGEN], 1u);
;             else XB_SPIN(xb_ld(&bar[XB_TOPGEN]) == tg, bar);
;             __builtin_amdgcn_fence(__ATOMIC_ACQUIRE, "agent");
;             xb_add(&bar[XB_XGEN(b.x)], 1u);
;             asm volatile("s_waitcnt vmcnt(0)" ::: "memory");
;         } else {
;             XB_SPIN(xb_ld(&bar[XB_XGEN(b.x)]) == gen, bar);
;             __builtin_amdgcn_fence(__ATOMIC_ACQUIRE, "agent");
;             asm volatile("s_waitcnt vmcnt(0)" ::: "memory");
.LBB0_2545:
	s_or_b64 exec, exec, s[6:7]
	v_cvt_f32_u32_e32 v4, v2
	s_waitcnt vmcnt(0)
	v_readfirstlane_b32 s4, v3
	v_sub_u32_e32 v3, 0, v2
	v_rcp_iflag_f32_e32 v4, v4
	v_add_u32_e32 v5, s4, v1
	v_mul_f32_e32 v4, 0x4f7ffffe, v4
	v_cvt_u32_f32_e32 v4, v4
	v_mul_lo_u32 v1, v3, v4
	v_mul_hi_u32 v1, v4, v1
	v_add_u32_e32 v1, v4, v1
	v_mul_hi_u32 v1, v5, v1
	v_mul_lo_u32 v3, v1, v2
	v_sub_u32_e32 v3, v5, v3
	v_add_u32_e32 v4, 1, v1
	v_cmp_ge_u32_e32 vcc, v3, v2
	s_nop 1
	v_cndmask_b32_e32 v1, v1, v4, vcc
	v_sub_u32_e32 v4, v3, v2
	v_cndmask_b32_e32 v3, v3, v4, vcc
	v_add_u32_e32 v4, 1, v1
	v_cmp_ge_u32_e32 vcc, v3, v2
	v_add_u32_e32 v3, 1, v5
	s_nop 0
	v_cndmask_b32_e32 v1, v1, v4, vcc
	v_mul_lo_u32 v4, v2, v1
	v_add_u32_e32 v2, v4, v2
	v_cmp_ne_u32_e32 vcc, v3, v2
	s_and_saveexec_b64 s[4:5], vcc
	s_xor_b64 s[4:5], exec, s[4:5]
	s_cbranch_execz .LBB0_2559
	s_waitcnt lgkmcnt(0)
	buffer_inv sc1
	v_mov_b32_e32 v0, 0x2000
	global_load_dword v0, v0, s[2:3] offset:1024 sc1
	s_add_u32 s10, s2, 0x2400
	s_addc_u32 s11, s3, 0
	s_waitcnt vmcnt(0)
	v_cmp_eq_u32_e32 vcc, v0, v1
	s_and_saveexec_b64 s[6:7], vcc
	s_cbranch_execz .LBB0_2558
	s_add_u32 s8, s88, 0x4200
	s_addc_u32 s9, s89, 0
	s_mov_b32 s22, 1
	s_mov_b64 s[12:13], 0
	v_mov_b32_e32 v0, 0
	s_branch .LBB0_2549

; __device__ __forceinline__ unsigned xb_ld(unsigned* p)              { return __hip_atomic_load(p, __ATOMIC_RELAXED, __HIP_MEMORY_SCOPE_AGENT); }
; #define XB_SPIN(cond, bar) do { unsigned _sp = 0; while (cond) { __builtin_amdgcn_s_sleep(1); \
;     if ((++_sp & 255u) == 0u) { if (xb_ld(&(bar)[XB_TMO])) break; if (_sp > XB_SPIN_CAP) { atomicAdd(&(bar)[XB_TMO], 1u); break; } } } } while (0)
; __device__ __forceinline__ void xcd_barrier(const XcdBarrier& b) {
;     ...
;             XB_SPIN(xb_ld(&bar[XB_XGEN(b.x)]) == gen, bar);
;             __builtin_amdgcn_fence(__ATOMIC_ACQUIRE, "agent");
;             asm volatile("s_waitcnt vmcnt(0)" ::: "memory");
.LBB0_2558:
	s_or_b64 exec, exec, s[6:7]
	s_waitcnt vmcnt(0)
	s_waitcnt vmcnt(0)
